# added P0 next-row prefetch (rows of the next iteration loaded during the current one) on top of the ln1 reduce-scatter DPP version
# speedup vs baseline: 1.0018x; 1.0018x over previous
.LBB0_35:
	s_or_b64 exec, exec, s[0:1]
	s_add_u32 s0, s66, 0x800000
	s_addc_u32 s1, s67, 0
	v_writelane_b32 v253, s0, 35
	s_cmp_lt_i32 s80, 0xc000
	s_cselect_b64 s[92:93], -1, 0
	v_writelane_b32 v253, s1, 36
	s_cmp_gt_i32 s80, 0xbfff
	v_xor_b32_e32 v245, 1, v174
	v_and_b32_e32 v246, 64, v174
	v_xor_b32_e32 v244, 2, v174
	v_xor_b32_e32 v243, 4, v174
	v_xor_b32_e32 v242, 8, v174
	v_xor_b32_e32 v241, 16, v174
	v_xor_b32_e32 v240, 32, v174
	s_waitcnt lgkmcnt(0)
	s_barrier
	s_cbranch_scc1 .LBB0_40
	v_bfrev_b32_e32 v1, v2
	v_lshrrev_b32_e32 v1, 26, v1
	v_readlane_b32 s16, v253, 0
	v_and_b32_e32 v4, 60, v1
	v_readlane_b32 s26, v253, 10
	v_readlane_b32 s27, v253, 11
	v_readlane_b32 s0, v253, 35
	v_mov_b32_e32 v5, 0
	v_readlane_b32 s1, v253, 36
	v_ashrrev_i32_e32 v3, 31, v2
	v_readlane_b32 s20, v253, 4
	global_load_dword v1, v4, s[26:27]
	v_lshl_add_u64 v[38:39], s[0:1], 0, v[4:5]
	v_lshl_add_u64 v[4:5], v[2:3], 3, s[66:67]
	s_mov_b64 s[0:1], 0x19400000
	v_lshl_add_u64 v[40:41], v[4:5], 0, s[0:1]
	v_and_b32_e32 v4, 1, v2
	v_cmp_eq_u32_e32 vcc, 0, v4
	v_add_u32_e32 v4, 64, v246
	v_cmp_lt_i32_e64 s[0:1], v245, v4
	v_cmp_lt_i32_e64 s[4:5], v244, v4
	v_cmp_lt_i32_e64 s[6:7], v242, v4
	v_cndmask_b32_e64 v5, v174, v245, s[0:1]
	v_lshlrev_b32_e32 v46, 2, v5
	v_and_b32_e32 v5, 2, v2
	v_cmp_eq_u32_e64 s[0:1], 0, v5
	v_cndmask_b32_e64 v5, v174, v244, s[4:5]
	v_lshlrev_b32_e32 v47, 2, v5
	v_and_b32_e32 v5, 4, v2
	v_cmp_lt_i32_e64 s[4:5], v243, v4
	v_cmp_eq_u32_e64 s[8:9], 0, v5
	v_readlane_b32 s21, v253, 5
	v_cndmask_b32_e64 v5, v174, v243, s[4:5]
	v_lshlrev_b32_e32 v48, 2, v5
	v_and_b32_e32 v5, 8, v2
	v_cmp_eq_u32_e64 s[4:5], 0, v5
	v_cndmask_b32_e64 v5, v174, v242, s[6:7]
	v_cmp_lt_i32_e64 s[6:7], v241, v4
	v_lshlrev_b32_e32 v49, 2, v5
	v_readlane_b32 s22, v253, 6
	v_cndmask_b32_e64 v5, v174, v241, s[6:7]
	v_cmp_lt_i32_e64 s[6:7], v240, v4
	v_readlane_b32 s23, v253, 7
	v_readlane_b32 s24, v253, 8
	v_cndmask_b32_e64 v4, v174, v240, s[6:7]
	v_lshl_add_u32 v44, v2, 4, 0
	v_lshlrev_b32_e32 v50, 2, v5
	v_lshlrev_b32_e32 v51, 2, v4
	v_cmp_gt_i32_e64 s[6:7], 16, v2
	v_lshlrev_b64 v[42:43], 4, v[2:3]
	s_mov_b32 s20, 0xbfb8aa3b
	s_mov_b32 s21, 0x3f2aaaab
	v_mov_b32_e32 v52, 0x3ecc95a3
	s_mov_b32 s22, 0x3f317218
	s_mov_b32 s23, 0x7f800000
	s_mov_b32 s24, 0x33800000
	v_mov_b32_e32 v53, 0x7f800000
	v_mov_b32_e32 v54, 0x7fc00000
	v_mov_b32_e32 v55, 0xff800000
	s_mov_b32 s16, s80
	v_readlane_b32 s17, v253, 1
	v_readlane_b32 s18, v253, 2
	v_readlane_b32 s19, v253, 3
	v_readlane_b32 s25, v253, 9
	v_readlane_b32 s28, v253, 12
	v_readlane_b32 s29, v253, 13
	v_readlane_b32 s30, v253, 14
	v_readlane_b32 s31, v253, 15
	v_readlane_b32 s36, v253, 0
	v_readlane_b32 s37, v253, 1
	v_readlane_b32 s38, v253, 2
	v_readlane_b32 s39, v253, 3
	s_nop 3
	s_mov_b32 s53, s16
	s_add_i32 s54, s53, s78
	s_cmp_lt_i32 s54, 0xc000
	s_cselect_b32 s54, s54, s53
	s_add_i32 s56, s53, 0xffff8000
	s_cmp_lt_i32 s53, 0x8000
	s_cselect_b32 s56, s53, s56
	s_cselect_b32 s89, s37, s39
	s_cselect_b32 s88, s36, s38
	s_lshl_b32 s56, s56, 12
	s_add_u32 s88, s88, s56
	s_addc_u32 s89, s89, 0
	s_add_i32 s57, s54, 0xffff8000
	s_cmp_lt_i32 s54, 0x8000
	s_cselect_b32 s57, s54, s57
	s_cselect_b32 s91, s37, s39
	s_cselect_b32 s90, s36, s38
	s_lshl_b32 s57, s57, 12
	s_add_u32 s90, s90, s57
	s_addc_u32 s91, s91, 0
	global_load_dwordx4 v[26:29], v42, s[88:89]
	global_load_dwordx4 v[22:25], v42, s[88:89] offset:1024
	global_load_dwordx4 v[176:179], v42, s[88:89] offset:2048
	global_load_dwordx4 v[180:183], v42, s[88:89] offset:3072
	global_load_dwordx4 v[30:33], v42, s[90:91]
	global_load_dwordx4 v[18:21], v42, s[90:91] offset:1024
	global_load_dwordx4 v[184:187], v42, s[90:91] offset:2048
	global_load_dwordx4 v[188:191], v42, s[90:91] offset:3072
	s_waitcnt vmcnt(0)
	s_branch .LBB0_38

.LBB0_38:
	s_add_i32 s25, s16, s78
	s_cmp_lt_i32 s25, 0xc000
	s_cselect_b32 s14, s25, s16
	s_add_i32 s10, s16, 0xffff8000
	s_ashr_i32 s17, s16, 31
	s_cmp_lt_i32 s16, 0x8000
	v_readlane_b32 s36, v253, 0
	s_cselect_b32 s11, s17, 0
	s_cselect_b32 s10, s16, s10
	v_readlane_b32 s37, v253, 1
	v_readlane_b32 s38, v253, 2
	v_readlane_b32 s39, v253, 3
	s_cselect_b32 s15, s37, s39
	s_cselect_b32 s18, s36, s38
	s_lshl_b64 s[10:11], s[10:11], 12
	s_add_u32 s10, s18, s10
	s_addc_u32 s11, s15, s11
	s_waitcnt lgkmcnt(0)
	s_add_i32 s10, s14, 0xffff8000
	s_ashr_i32 s15, s14, 31
	s_cmp_lt_i32 s14, 0x8000
	s_cselect_b32 s11, s15, 0
	s_cselect_b32 s10, s14, s10
	s_cselect_b32 s18, s37, s39
	s_cselect_b32 s19, s36, s38
	s_lshl_b64 s[10:11], s[10:11], 12
	s_add_u32 s10, s19, s10
	s_addc_u32 s11, s18, s11
	s_lshl_b64 s[10:11], s[16:17], 11
	s_lshl_b64 s[18:19], s[14:15], 11
	v_lshl_add_u64 v[34:35], v[40:41], 0, s[10:11]
	v_lshl_add_u64 v[36:37], v[40:41], 0, s[18:19]
	v_readlane_b32 s40, v253, 4
	v_readlane_b32 s41, v253, 5
	v_readlane_b32 s42, v253, 6
	v_readlane_b32 s43, v253, 7
	v_readlane_b32 s44, v253, 8
	v_readlane_b32 s45, v253, 9
	v_readlane_b32 s46, v253, 10
	v_readlane_b32 s47, v253, 11
	v_readlane_b32 s48, v253, 12
	v_readlane_b32 s49, v253, 13
	v_readlane_b32 s50, v253, 14
	v_readlane_b32 s51, v253, 15
	s_waitcnt vmcnt(2)
	v_mov_b64_e32 v[10:11], v[176:177]
	v_mov_b64_e32 v[12:13], v[178:179]
	v_mov_b64_e32 v[2:3], v[180:181]
	v_mov_b64_e32 v[4:5], v[182:183]
	v_mov_b64_e32 v[14:15], v[184:185]
	v_mov_b64_e32 v[16:17], v[186:187]
	v_mov_b64_e32 v[6:7], v[188:189]
	v_mov_b64_e32 v[8:9], v[190:191]
	v_cvt_pk_bf16_f32 v56, v26, v27
	v_cvt_pk_bf16_f32 v57, v28, v29
	s_waitcnt vmcnt(6)
	v_cvt_pk_bf16_f32 v58, v22, v23
	v_cvt_pk_bf16_f32 v59, v24, v25
	s_waitcnt vmcnt(5)
	v_cvt_pk_bf16_f32 v60, v10, v11
	v_cvt_pk_bf16_f32 v61, v12, v13
	s_waitcnt vmcnt(4)
	v_cvt_pk_bf16_f32 v62, v2, v3
	v_cvt_pk_bf16_f32 v63, v4, v5
	global_store_dwordx2 v[34:35], v[56:57], off
	global_store_dwordx2 v[34:35], v[58:59], off offset:512
	global_store_dwordx2 v[34:35], v[60:61], off offset:1024
	global_store_dwordx2 v[34:35], v[62:63], off offset:1536
	s_waitcnt vmcnt(7)
	v_cvt_pk_bf16_f32 v34, v30, v31
	v_cvt_pk_bf16_f32 v35, v32, v33
	s_waitcnt vmcnt(6)
	v_cvt_pk_bf16_f32 v56, v18, v19
	v_cvt_pk_bf16_f32 v57, v20, v21
	s_waitcnt vmcnt(5)
	v_cvt_pk_bf16_f32 v58, v14, v15
	v_cvt_pk_bf16_f32 v59, v16, v17
	s_waitcnt vmcnt(4)
	v_cvt_pk_bf16_f32 v60, v6, v7
	v_cvt_pk_bf16_f32 v61, v8, v9
	global_store_dwordx2 v[36:37], v[34:35], off
	global_store_dwordx2 v[36:37], v[56:57], off offset:512
	global_store_dwordx2 v[36:37], v[58:59], off offset:1024
	global_store_dwordx2 v[36:37], v[60:61], off offset:1536
	ds_read_b128 v[176:179], v44 offset:0
	ds_read_b128 v[180:183], v44 offset:1024
	ds_read_b128 v[184:187], v44 offset:2048
	ds_read_b128 v[188:191], v44 offset:3072
	ds_read_b128 v[192:195], v44 offset:4096
	ds_read_b128 v[196:199], v44 offset:5120
	ds_read_b128 v[200:203], v44 offset:6144
	ds_read_b128 v[204:207], v44 offset:7168
	s_waitcnt lgkmcnt(4)
	v_pk_mul_f32 v[208:209], v[26:27], v[176:177]
	v_pk_mul_f32 v[210:211], v[30:31], v[176:177]
	v_pk_fma_f32 v[208:209], v[28:29], v[178:179], v[208:209]
	v_pk_fma_f32 v[210:211], v[32:33], v[178:179], v[210:211]
	v_pk_fma_f32 v[208:209], v[22:23], v[180:181], v[208:209]
	v_pk_fma_f32 v[210:211], v[18:19], v[180:181], v[210:211]
	v_pk_fma_f32 v[208:209], v[24:25], v[182:183], v[208:209]
	v_pk_fma_f32 v[210:211], v[20:21], v[182:183], v[210:211]
	v_pk_fma_f32 v[208:209], v[10:11], v[184:185], v[208:209]
	v_pk_fma_f32 v[210:211], v[14:15], v[184:185], v[210:211]
	v_pk_fma_f32 v[208:209], v[12:13], v[186:187], v[208:209]
	v_pk_fma_f32 v[210:211], v[16:17], v[186:187], v[210:211]
	v_pk_fma_f32 v[208:209], v[2:3], v[188:189], v[208:209]
	v_pk_fma_f32 v[210:211], v[6:7], v[188:189], v[210:211]
	v_pk_fma_f32 v[208:209], v[4:5], v[190:191], v[208:209]
	v_pk_fma_f32 v[210:211], v[8:9], v[190:191], v[210:211]
	v_add_f32_e32 v142, v208, v209
	v_add_f32_e32 v143, v210, v211
	ds_read_b128 v[176:179], v44 offset:8192
	ds_read_b128 v[180:183], v44 offset:9216
	ds_read_b128 v[184:187], v44 offset:10240
	ds_read_b128 v[188:191], v44 offset:11264
	s_waitcnt lgkmcnt(4)
	v_pk_mul_f32 v[208:209], v[26:27], v[192:193]
	v_pk_mul_f32 v[210:211], v[30:31], v[192:193]
	v_pk_fma_f32 v[208:209], v[28:29], v[194:195], v[208:209]
	v_pk_fma_f32 v[210:211], v[32:33], v[194:195], v[210:211]
	v_pk_fma_f32 v[208:209], v[22:23], v[196:197], v[208:209]
	v_pk_fma_f32 v[210:211], v[18:19], v[196:197], v[210:211]
	v_pk_fma_f32 v[208:209], v[24:25], v[198:199], v[208:209]
	v_pk_fma_f32 v[210:211], v[20:21], v[198:199], v[210:211]
	v_pk_fma_f32 v[208:209], v[10:11], v[200:201], v[208:209]
	v_pk_fma_f32 v[210:211], v[14:15], v[200:201], v[210:211]
	v_pk_fma_f32 v[208:209], v[12:13], v[202:203], v[208:209]
	v_pk_fma_f32 v[210:211], v[16:17], v[202:203], v[210:211]
	v_pk_fma_f32 v[208:209], v[2:3], v[204:205], v[208:209]
	v_pk_fma_f32 v[210:211], v[6:7], v[204:205], v[210:211]
	v_pk_fma_f32 v[208:209], v[4:5], v[206:207], v[208:209]
	v_pk_fma_f32 v[210:211], v[8:9], v[206:207], v[210:211]
	v_add_f32_e32 v144, v208, v209
	v_add_f32_e32 v145, v210, v211
	ds_read_b128 v[192:195], v44 offset:12288
	ds_read_b128 v[196:199], v44 offset:13312
	ds_read_b128 v[200:203], v44 offset:14336
	ds_read_b128 v[204:207], v44 offset:15360
	s_waitcnt lgkmcnt(4)
	v_pk_mul_f32 v[208:209], v[26:27], v[176:177]
	v_pk_mul_f32 v[210:211], v[30:31], v[176:177]
	v_pk_fma_f32 v[208:209], v[28:29], v[178:179], v[208:209]
	v_pk_fma_f32 v[210:211], v[32:33], v[178:179], v[210:211]
	v_pk_fma_f32 v[208:209], v[22:23], v[180:181], v[208:209]
	v_pk_fma_f32 v[210:211], v[18:19], v[180:181], v[210:211]
	v_pk_fma_f32 v[208:209], v[24:25], v[182:183], v[208:209]
	v_pk_fma_f32 v[210:211], v[20:21], v[182:183], v[210:211]
	v_pk_fma_f32 v[208:209], v[10:11], v[184:185], v[208:209]
	v_pk_fma_f32 v[210:211], v[14:15], v[184:185], v[210:211]
	v_pk_fma_f32 v[208:209], v[12:13], v[186:187], v[208:209]
	v_pk_fma_f32 v[210:211], v[16:17], v[186:187], v[210:211]
	v_pk_fma_f32 v[208:209], v[2:3], v[188:189], v[208:209]
	v_pk_fma_f32 v[210:211], v[6:7], v[188:189], v[210:211]
	v_pk_fma_f32 v[208:209], v[4:5], v[190:191], v[208:209]
	v_pk_fma_f32 v[210:211], v[8:9], v[190:191], v[210:211]
	v_add_f32_e32 v146, v208, v209
	v_add_f32_e32 v147, v210, v211
	ds_read_b128 v[176:179], v44 offset:16384
	ds_read_b128 v[180:183], v44 offset:17408
	ds_read_b128 v[184:187], v44 offset:18432
	ds_read_b128 v[188:191], v44 offset:19456
	s_waitcnt lgkmcnt(4)
	v_pk_mul_f32 v[208:209], v[26:27], v[192:193]
	v_pk_mul_f32 v[210:211], v[30:31], v[192:193]
	v_pk_fma_f32 v[208:209], v[28:29], v[194:195], v[208:209]
	v_pk_fma_f32 v[210:211], v[32:33], v[194:195], v[210:211]
	v_pk_fma_f32 v[208:209], v[22:23], v[196:197], v[208:209]
	v_pk_fma_f32 v[210:211], v[18:19], v[196:197], v[210:211]
	v_pk_fma_f32 v[208:209], v[24:25], v[198:199], v[208:209]
	v_pk_fma_f32 v[210:211], v[20:21], v[198:199], v[210:211]
	v_pk_fma_f32 v[208:209], v[10:11], v[200:201], v[208:209]
	v_pk_fma_f32 v[210:211], v[14:15], v[200:201], v[210:211]
	v_pk_fma_f32 v[208:209], v[12:13], v[202:203], v[208:209]
	v_pk_fma_f32 v[210:211], v[16:17], v[202:203], v[210:211]
	v_pk_fma_f32 v[208:209], v[2:3], v[204:205], v[208:209]
	v_pk_fma_f32 v[210:211], v[6:7], v[204:205], v[210:211]
	v_pk_fma_f32 v[208:209], v[4:5], v[206:207], v[208:209]
	v_pk_fma_f32 v[210:211], v[8:9], v[206:207], v[210:211]
	v_add_f32_e32 v148, v208, v209
	v_add_f32_e32 v149, v210, v211
	ds_read_b128 v[192:195], v44 offset:20480
	ds_read_b128 v[196:199], v44 offset:21504
	ds_read_b128 v[200:203], v44 offset:22528
	ds_read_b128 v[204:207], v44 offset:23552
	s_waitcnt lgkmcnt(4)
	v_pk_mul_f32 v[208:209], v[26:27], v[176:177]
	v_pk_mul_f32 v[210:211], v[30:31], v[176:177]
	v_pk_fma_f32 v[208:209], v[28:29], v[178:179], v[208:209]
	v_pk_fma_f32 v[210:211], v[32:33], v[178:179], v[210:211]
	v_pk_fma_f32 v[208:209], v[22:23], v[180:181], v[208:209]
	v_pk_fma_f32 v[210:211], v[18:19], v[180:181], v[210:211]
	v_pk_fma_f32 v[208:209], v[24:25], v[182:183], v[208:209]
	v_pk_fma_f32 v[210:211], v[20:21], v[182:183], v[210:211]
	v_pk_fma_f32 v[208:209], v[10:11], v[184:185], v[208:209]
	v_pk_fma_f32 v[210:211], v[14:15], v[184:185], v[210:211]
	v_pk_fma_f32 v[208:209], v[12:13], v[186:187], v[208:209]
	v_pk_fma_f32 v[210:211], v[16:17], v[186:187], v[210:211]
	v_pk_fma_f32 v[208:209], v[2:3], v[188:189], v[208:209]
	v_pk_fma_f32 v[210:211], v[6:7], v[188:189], v[210:211]
	v_pk_fma_f32 v[208:209], v[4:5], v[190:191], v[208:209]
	v_pk_fma_f32 v[210:211], v[8:9], v[190:191], v[210:211]
	v_add_f32_e32 v150, v208, v209
	v_add_f32_e32 v151, v210, v211
	ds_read_b128 v[176:179], v44 offset:24576
	ds_read_b128 v[180:183], v44 offset:25600
	ds_read_b128 v[184:187], v44 offset:26624
	ds_read_b128 v[188:191], v44 offset:27648
	s_waitcnt lgkmcnt(4)
	v_pk_mul_f32 v[208:209], v[26:27], v[192:193]
	v_pk_mul_f32 v[210:211], v[30:31], v[192:193]
	v_pk_fma_f32 v[208:209], v[28:29], v[194:195], v[208:209]
	v_pk_fma_f32 v[210:211], v[32:33], v[194:195], v[210:211]
	v_pk_fma_f32 v[208:209], v[22:23], v[196:197], v[208:209]
	v_pk_fma_f32 v[210:211], v[18:19], v[196:197], v[210:211]
	v_pk_fma_f32 v[208:209], v[24:25], v[198:199], v[208:209]
	v_pk_fma_f32 v[210:211], v[20:21], v[198:199], v[210:211]
	v_pk_fma_f32 v[208:209], v[10:11], v[200:201], v[208:209]
	v_pk_fma_f32 v[210:211], v[14:15], v[200:201], v[210:211]
	v_pk_fma_f32 v[208:209], v[12:13], v[202:203], v[208:209]
	v_pk_fma_f32 v[210:211], v[16:17], v[202:203], v[210:211]
	v_pk_fma_f32 v[208:209], v[2:3], v[204:205], v[208:209]
	v_pk_fma_f32 v[210:211], v[6:7], v[204:205], v[210:211]
	v_pk_fma_f32 v[208:209], v[4:5], v[206:207], v[208:209]
	v_pk_fma_f32 v[210:211], v[8:9], v[206:207], v[210:211]
	v_add_f32_e32 v152, v208, v209
	v_add_f32_e32 v153, v210, v211
	ds_read_b128 v[192:195], v44 offset:28672
	ds_read_b128 v[196:199], v44 offset:29696
	ds_read_b128 v[200:203], v44 offset:30720
	ds_read_b128 v[204:207], v44 offset:31744
	s_waitcnt lgkmcnt(4)
	v_pk_mul_f32 v[208:209], v[26:27], v[176:177]
	v_pk_mul_f32 v[210:211], v[30:31], v[176:177]
	v_pk_fma_f32 v[208:209], v[28:29], v[178:179], v[208:209]
	v_pk_fma_f32 v[210:211], v[32:33], v[178:179], v[210:211]
	v_pk_fma_f32 v[208:209], v[22:23], v[180:181], v[208:209]
	v_pk_fma_f32 v[210:211], v[18:19], v[180:181], v[210:211]
	v_pk_fma_f32 v[208:209], v[24:25], v[182:183], v[208:209]
	v_pk_fma_f32 v[210:211], v[20:21], v[182:183], v[210:211]
	v_pk_fma_f32 v[208:209], v[10:11], v[184:185], v[208:209]
	v_pk_fma_f32 v[210:211], v[14:15], v[184:185], v[210:211]
	v_pk_fma_f32 v[208:209], v[12:13], v[186:187], v[208:209]
	v_pk_fma_f32 v[210:211], v[16:17], v[186:187], v[210:211]
	v_pk_fma_f32 v[208:209], v[2:3], v[188:189], v[208:209]
	v_pk_fma_f32 v[210:211], v[6:7], v[188:189], v[210:211]
	v_pk_fma_f32 v[208:209], v[4:5], v[190:191], v[208:209]
	v_pk_fma_f32 v[210:211], v[8:9], v[190:191], v[210:211]
	v_add_f32_e32 v154, v208, v209
	v_add_f32_e32 v155, v210, v211
	ds_read_b128 v[176:179], v44 offset:32768
	ds_read_b128 v[180:183], v44 offset:33792
	ds_read_b128 v[184:187], v44 offset:34816
	ds_read_b128 v[188:191], v44 offset:35840
	s_waitcnt lgkmcnt(4)
	v_pk_mul_f32 v[208:209], v[26:27], v[192:193]
	v_pk_mul_f32 v[210:211], v[30:31], v[192:193]
	v_pk_fma_f32 v[208:209], v[28:29], v[194:195], v[208:209]
	v_pk_fma_f32 v[210:211], v[32:33], v[194:195], v[210:211]
	v_pk_fma_f32 v[208:209], v[22:23], v[196:197], v[208:209]
	v_pk_fma_f32 v[210:211], v[18:19], v[196:197], v[210:211]
	v_pk_fma_f32 v[208:209], v[24:25], v[198:199], v[208:209]
	v_pk_fma_f32 v[210:211], v[20:21], v[198:199], v[210:211]
	v_pk_fma_f32 v[208:209], v[10:11], v[200:201], v[208:209]
	v_pk_fma_f32 v[210:211], v[14:15], v[200:201], v[210:211]
	v_pk_fma_f32 v[208:209], v[12:13], v[202:203], v[208:209]
	v_pk_fma_f32 v[210:211], v[16:17], v[202:203], v[210:211]
	v_pk_fma_f32 v[208:209], v[2:3], v[204:205], v[208:209]
	v_pk_fma_f32 v[210:211], v[6:7], v[204:205], v[210:211]
	v_pk_fma_f32 v[208:209], v[4:5], v[206:207], v[208:209]
	v_pk_fma_f32 v[210:211], v[8:9], v[206:207], v[210:211]
	v_add_f32_e32 v156, v208, v209
	v_add_f32_e32 v157, v210, v211
	ds_read_b128 v[192:195], v44 offset:36864
	ds_read_b128 v[196:199], v44 offset:37888
	ds_read_b128 v[200:203], v44 offset:38912
	ds_read_b128 v[204:207], v44 offset:39936
	s_waitcnt lgkmcnt(4)
	v_pk_mul_f32 v[208:209], v[26:27], v[176:177]
	v_pk_mul_f32 v[210:211], v[30:31], v[176:177]
	v_pk_fma_f32 v[208:209], v[28:29], v[178:179], v[208:209]
	v_pk_fma_f32 v[210:211], v[32:33], v[178:179], v[210:211]
	v_pk_fma_f32 v[208:209], v[22:23], v[180:181], v[208:209]
	v_pk_fma_f32 v[210:211], v[18:19], v[180:181], v[210:211]
	v_pk_fma_f32 v[208:209], v[24:25], v[182:183], v[208:209]
	v_pk_fma_f32 v[210:211], v[20:21], v[182:183], v[210:211]
	v_pk_fma_f32 v[208:209], v[10:11], v[184:185], v[208:209]
	v_pk_fma_f32 v[210:211], v[14:15], v[184:185], v[210:211]
	v_pk_fma_f32 v[208:209], v[12:13], v[186:187], v[208:209]
	v_pk_fma_f32 v[210:211], v[16:17], v[186:187], v[210:211]
	v_pk_fma_f32 v[208:209], v[2:3], v[188:189], v[208:209]
	v_pk_fma_f32 v[210:211], v[6:7], v[188:189], v[210:211]
	v_pk_fma_f32 v[208:209], v[4:5], v[190:191], v[208:209]
	v_pk_fma_f32 v[210:211], v[8:9], v[190:191], v[210:211]
	v_add_f32_e32 v158, v208, v209
	v_add_f32_e32 v159, v210, v211
	ds_read_b128 v[176:179], v44 offset:40960
	ds_read_b128 v[180:183], v44 offset:41984
	ds_read_b128 v[184:187], v44 offset:43008
	ds_read_b128 v[188:191], v44 offset:44032
	s_waitcnt lgkmcnt(4)
	v_pk_mul_f32 v[208:209], v[26:27], v[192:193]
	v_pk_mul_f32 v[210:211], v[30:31], v[192:193]
	v_pk_fma_f32 v[208:209], v[28:29], v[194:195], v[208:209]
	v_pk_fma_f32 v[210:211], v[32:33], v[194:195], v[210:211]
	v_pk_fma_f32 v[208:209], v[22:23], v[196:197], v[208:209]
	v_pk_fma_f32 v[210:211], v[18:19], v[196:197], v[210:211]
	v_pk_fma_f32 v[208:209], v[24:25], v[198:199], v[208:209]
	v_pk_fma_f32 v[210:211], v[20:21], v[198:199], v[210:211]
	v_pk_fma_f32 v[208:209], v[10:11], v[200:201], v[208:209]
	v_pk_fma_f32 v[210:211], v[14:15], v[200:201], v[210:211]
	v_pk_fma_f32 v[208:209], v[12:13], v[202:203], v[208:209]
	v_pk_fma_f32 v[210:211], v[16:17], v[202:203], v[210:211]
	v_pk_fma_f32 v[208:209], v[2:3], v[204:205], v[208:209]
	v_pk_fma_f32 v[210:211], v[6:7], v[204:205], v[210:211]
	v_pk_fma_f32 v[208:209], v[4:5], v[206:207], v[208:209]
	v_pk_fma_f32 v[210:211], v[8:9], v[206:207], v[210:211]
	v_add_f32_e32 v160, v208, v209
	v_add_f32_e32 v161, v210, v211
	ds_read_b128 v[192:195], v44 offset:45056
	ds_read_b128 v[196:199], v44 offset:46080
	ds_read_b128 v[200:203], v44 offset:47104
	ds_read_b128 v[204:207], v44 offset:48128
	s_waitcnt lgkmcnt(4)
	v_pk_mul_f32 v[208:209], v[26:27], v[176:177]
	v_pk_mul_f32 v[210:211], v[30:31], v[176:177]
	v_pk_fma_f32 v[208:209], v[28:29], v[178:179], v[208:209]
	v_pk_fma_f32 v[210:211], v[32:33], v[178:179], v[210:211]
	v_pk_fma_f32 v[208:209], v[22:23], v[180:181], v[208:209]
	v_pk_fma_f32 v[210:211], v[18:19], v[180:181], v[210:211]
	v_pk_fma_f32 v[208:209], v[24:25], v[182:183], v[208:209]
	v_pk_fma_f32 v[210:211], v[20:21], v[182:183], v[210:211]
	v_pk_fma_f32 v[208:209], v[10:11], v[184:185], v[208:209]
	v_pk_fma_f32 v[210:211], v[14:15], v[184:185], v[210:211]
	v_pk_fma_f32 v[208:209], v[12:13], v[186:187], v[208:209]
	v_pk_fma_f32 v[210:211], v[16:17], v[186:187], v[210:211]
	v_pk_fma_f32 v[208:209], v[2:3], v[188:189], v[208:209]
	v_pk_fma_f32 v[210:211], v[6:7], v[188:189], v[210:211]
	v_pk_fma_f32 v[208:209], v[4:5], v[190:191], v[208:209]
	v_pk_fma_f32 v[210:211], v[8:9], v[190:191], v[210:211]
	v_add_f32_e32 v162, v208, v209
	v_add_f32_e32 v163, v210, v211
	ds_read_b128 v[176:179], v44 offset:49152
	ds_read_b128 v[180:183], v44 offset:50176
	ds_read_b128 v[184:187], v44 offset:51200
	ds_read_b128 v[188:191], v44 offset:52224
	s_waitcnt lgkmcnt(4)
	v_pk_mul_f32 v[208:209], v[26:27], v[192:193]
	v_pk_mul_f32 v[210:211], v[30:31], v[192:193]
	v_pk_fma_f32 v[208:209], v[28:29], v[194:195], v[208:209]
	v_pk_fma_f32 v[210:211], v[32:33], v[194:195], v[210:211]
	v_pk_fma_f32 v[208:209], v[22:23], v[196:197], v[208:209]
	v_pk_fma_f32 v[210:211], v[18:19], v[196:197], v[210:211]
	v_pk_fma_f32 v[208:209], v[24:25], v[198:199], v[208:209]
	v_pk_fma_f32 v[210:211], v[20:21], v[198:199], v[210:211]
	v_pk_fma_f32 v[208:209], v[10:11], v[200:201], v[208:209]
	v_pk_fma_f32 v[210:211], v[14:15], v[200:201], v[210:211]
	v_pk_fma_f32 v[208:209], v[12:13], v[202:203], v[208:209]
	v_pk_fma_f32 v[210:211], v[16:17], v[202:203], v[210:211]
	v_pk_fma_f32 v[208:209], v[2:3], v[204:205], v[208:209]
	v_pk_fma_f32 v[210:211], v[6:7], v[204:205], v[210:211]
	v_pk_fma_f32 v[208:209], v[4:5], v[206:207], v[208:209]
	v_pk_fma_f32 v[210:211], v[8:9], v[206:207], v[210:211]
	v_add_f32_e32 v164, v208, v209
	v_add_f32_e32 v165, v210, v211
	ds_read_b128 v[192:195], v44 offset:53248
	ds_read_b128 v[196:199], v44 offset:54272
	ds_read_b128 v[200:203], v44 offset:55296
	ds_read_b128 v[204:207], v44 offset:56320
	s_waitcnt lgkmcnt(4)
	v_pk_mul_f32 v[208:209], v[26:27], v[176:177]
	v_pk_mul_f32 v[210:211], v[30:31], v[176:177]
	v_pk_fma_f32 v[208:209], v[28:29], v[178:179], v[208:209]
	v_pk_fma_f32 v[210:211], v[32:33], v[178:179], v[210:211]
	v_pk_fma_f32 v[208:209], v[22:23], v[180:181], v[208:209]
	v_pk_fma_f32 v[210:211], v[18:19], v[180:181], v[210:211]
	v_pk_fma_f32 v[208:209], v[24:25], v[182:183], v[208:209]
	v_pk_fma_f32 v[210:211], v[20:21], v[182:183], v[210:211]
	v_pk_fma_f32 v[208:209], v[10:11], v[184:185], v[208:209]
	v_pk_fma_f32 v[210:211], v[14:15], v[184:185], v[210:211]
	v_pk_fma_f32 v[208:209], v[12:13], v[186:187], v[208:209]
	v_pk_fma_f32 v[210:211], v[16:17], v[186:187], v[210:211]
	v_pk_fma_f32 v[208:209], v[2:3], v[188:189], v[208:209]
	v_pk_fma_f32 v[210:211], v[6:7], v[188:189], v[210:211]
	v_pk_fma_f32 v[208:209], v[4:5], v[190:191], v[208:209]
	v_pk_fma_f32 v[210:211], v[8:9], v[190:191], v[210:211]
	v_add_f32_e32 v166, v208, v209
	v_add_f32_e32 v167, v210, v211
	ds_read_b128 v[176:179], v44 offset:57344
	ds_read_b128 v[180:183], v44 offset:58368
	ds_read_b128 v[184:187], v44 offset:59392
	ds_read_b128 v[188:191], v44 offset:60416
	s_waitcnt lgkmcnt(4)
	v_pk_mul_f32 v[208:209], v[26:27], v[192:193]
	v_pk_mul_f32 v[210:211], v[30:31], v[192:193]
	v_pk_fma_f32 v[208:209], v[28:29], v[194:195], v[208:209]
	v_pk_fma_f32 v[210:211], v[32:33], v[194:195], v[210:211]
	v_pk_fma_f32 v[208:209], v[22:23], v[196:197], v[208:209]
	v_pk_fma_f32 v[210:211], v[18:19], v[196:197], v[210:211]
	v_pk_fma_f32 v[208:209], v[24:25], v[198:199], v[208:209]
	v_pk_fma_f32 v[210:211], v[20:21], v[198:199], v[210:211]
	v_pk_fma_f32 v[208:209], v[10:11], v[200:201], v[208:209]
	v_pk_fma_f32 v[210:211], v[14:15], v[200:201], v[210:211]
	v_pk_fma_f32 v[208:209], v[12:13], v[202:203], v[208:209]
	v_pk_fma_f32 v[210:211], v[16:17], v[202:203], v[210:211]
	v_pk_fma_f32 v[208:209], v[2:3], v[204:205], v[208:209]
	v_pk_fma_f32 v[210:211], v[6:7], v[204:205], v[210:211]
	v_pk_fma_f32 v[208:209], v[4:5], v[206:207], v[208:209]
	v_pk_fma_f32 v[210:211], v[8:9], v[206:207], v[210:211]
	v_add_f32_e32 v168, v208, v209
	v_add_f32_e32 v169, v210, v211
	ds_read_b128 v[192:195], v44 offset:61440
	ds_read_b128 v[196:199], v44 offset:62464
	ds_read_b128 v[200:203], v44 offset:63488
	ds_read_b128 v[204:207], v44 offset:64512
	s_waitcnt lgkmcnt(4)
	v_pk_mul_f32 v[208:209], v[26:27], v[176:177]
	v_pk_mul_f32 v[210:211], v[30:31], v[176:177]
	v_pk_fma_f32 v[208:209], v[28:29], v[178:179], v[208:209]
	v_pk_fma_f32 v[210:211], v[32:33], v[178:179], v[210:211]
	v_pk_fma_f32 v[208:209], v[22:23], v[180:181], v[208:209]
	v_pk_fma_f32 v[210:211], v[18:19], v[180:181], v[210:211]
	v_pk_fma_f32 v[208:209], v[24:25], v[182:183], v[208:209]
	v_pk_fma_f32 v[210:211], v[20:21], v[182:183], v[210:211]
	v_pk_fma_f32 v[208:209], v[10:11], v[184:185], v[208:209]
	v_pk_fma_f32 v[210:211], v[14:15], v[184:185], v[210:211]
	v_pk_fma_f32 v[208:209], v[12:13], v[186:187], v[208:209]
	v_pk_fma_f32 v[210:211], v[16:17], v[186:187], v[210:211]
	v_pk_fma_f32 v[208:209], v[2:3], v[188:189], v[208:209]
	v_pk_fma_f32 v[210:211], v[6:7], v[188:189], v[210:211]
	v_pk_fma_f32 v[208:209], v[4:5], v[190:191], v[208:209]
	v_pk_fma_f32 v[210:211], v[8:9], v[190:191], v[210:211]
	v_add_f32_e32 v170, v208, v209
	v_add_f32_e32 v171, v210, v211
	s_waitcnt lgkmcnt(0)
	v_pk_mul_f32 v[208:209], v[26:27], v[192:193]
	v_pk_mul_f32 v[210:211], v[30:31], v[192:193]
	v_pk_fma_f32 v[208:209], v[28:29], v[194:195], v[208:209]
	v_pk_fma_f32 v[210:211], v[32:33], v[194:195], v[210:211]
	v_pk_fma_f32 v[208:209], v[22:23], v[196:197], v[208:209]
	v_pk_fma_f32 v[210:211], v[18:19], v[196:197], v[210:211]
	v_pk_fma_f32 v[208:209], v[24:25], v[198:199], v[208:209]
	v_pk_fma_f32 v[210:211], v[20:21], v[198:199], v[210:211]
	v_pk_fma_f32 v[208:209], v[10:11], v[200:201], v[208:209]
	v_pk_fma_f32 v[210:211], v[14:15], v[200:201], v[210:211]
	v_pk_fma_f32 v[208:209], v[12:13], v[202:203], v[208:209]
	v_pk_fma_f32 v[210:211], v[16:17], v[202:203], v[210:211]
	v_pk_fma_f32 v[208:209], v[2:3], v[204:205], v[208:209]
	v_pk_fma_f32 v[210:211], v[6:7], v[204:205], v[210:211]
	v_pk_fma_f32 v[208:209], v[4:5], v[206:207], v[208:209]
	v_pk_fma_f32 v[210:211], v[8:9], v[206:207], v[210:211]
	v_add_f32_e32 v172, v208, v209
	v_add_f32_e32 v173, v210, v211
	s_add_i32 s53, s25, s78
	s_cmp_lt_i32 s53, 0xc000
	s_cselect_b32 s53, s53, s16
	s_add_i32 s54, s53, s78
	s_cmp_lt_i32 s54, 0xc000
	s_cselect_b32 s54, s54, s53
	s_add_i32 s56, s53, 0xffff8000
	s_cmp_lt_i32 s53, 0x8000
	s_cselect_b32 s56, s53, s56
	s_cselect_b32 s89, s37, s39
	s_cselect_b32 s88, s36, s38
	s_lshl_b32 s56, s56, 12
	s_add_u32 s88, s88, s56
	s_addc_u32 s89, s89, 0
	s_add_i32 s57, s54, 0xffff8000
	s_cmp_lt_i32 s54, 0x8000
	s_cselect_b32 s57, s54, s57
	s_cselect_b32 s91, s37, s39
	s_cselect_b32 s90, s36, s38
	s_lshl_b32 s57, s57, 12
	s_add_u32 s90, s90, s57
	s_addc_u32 s91, s91, 0
	global_load_dwordx4 v[26:29], v42, s[88:89]
	global_load_dwordx4 v[22:25], v42, s[88:89] offset:1024
	global_load_dwordx4 v[176:179], v42, s[88:89] offset:2048
	global_load_dwordx4 v[180:183], v42, s[88:89] offset:3072
	global_load_dwordx4 v[30:33], v42, s[90:91]
	global_load_dwordx4 v[18:21], v42, s[90:91] offset:1024
	global_load_dwordx4 v[184:187], v42, s[90:91] offset:2048
	global_load_dwordx4 v[188:191], v42, s[90:91] offset:3072
	v_cndmask_b32_e32 v4, v142, v158, vcc
	ds_bpermute_b32 v4, v46, v4
	v_cndmask_b32_e32 v6, v144, v160, vcc
	ds_bpermute_b32 v6, v46, v6
	v_cndmask_b32_e32 v7, v146, v162, vcc
	ds_bpermute_b32 v7, v46, v7
	v_cndmask_b32_e32 v5, v158, v142, vcc
	s_waitcnt lgkmcnt(2)
	v_add_f32_e32 v4, v5, v4
	v_cndmask_b32_e32 v5, v160, v144, vcc
	s_waitcnt lgkmcnt(1)
	v_add_f32_e32 v5, v5, v6
	v_cndmask_b32_e32 v6, v162, v146, vcc
	s_waitcnt lgkmcnt(0)
	v_add_f32_e32 v6, v6, v7
	v_cndmask_b32_e32 v7, v148, v164, vcc
	ds_bpermute_b32 v7, v46, v7
	v_cndmask_b32_e32 v9, v150, v166, vcc
	ds_bpermute_b32 v9, v46, v9
	v_cndmask_b32_e32 v10, v152, v168, vcc
	ds_bpermute_b32 v10, v46, v10
	v_cndmask_b32_e32 v8, v164, v148, vcc
	s_waitcnt lgkmcnt(2)
	v_add_f32_e32 v7, v8, v7
	v_cndmask_b32_e32 v8, v166, v150, vcc
	s_waitcnt lgkmcnt(1)
	v_add_f32_e32 v8, v8, v9
	v_cndmask_b32_e32 v9, v168, v152, vcc
	v_cndmask_b32_e32 v13, v156, v172, vcc
	s_waitcnt lgkmcnt(0)
	v_add_f32_e32 v9, v9, v10
	v_cndmask_b32_e32 v10, v154, v170, vcc
	ds_bpermute_b32 v13, v46, v13
	ds_bpermute_b32 v10, v46, v10
	v_cndmask_b32_e32 v2, v172, v156, vcc
	v_cndmask_b32_e32 v12, v170, v154, vcc
	s_waitcnt lgkmcnt(1)
	v_add_f32_e32 v2, v2, v13
	v_cndmask_b32_e64 v14, v4, v8, s[0:1]
	s_waitcnt lgkmcnt(0)
	v_add_f32_e32 v10, v12, v10
	v_cndmask_b32_e64 v4, v8, v4, s[0:1]
	v_cndmask_b32_e64 v8, v5, v9, s[0:1]
	v_cndmask_b32_e64 v12, v7, v2, s[0:1]
	ds_bpermute_b32 v8, v47, v8
	ds_bpermute_b32 v12, v47, v12
	v_cndmask_b32_e64 v5, v9, v5, s[0:1]
	v_cndmask_b32_e64 v9, v6, v10, s[0:1]
	ds_bpermute_b32 v14, v47, v14
	ds_bpermute_b32 v9, v47, v9
	v_cndmask_b32_e64 v2, v2, v7, s[0:1]
	s_waitcnt lgkmcnt(3)
	v_add_f32_e32 v5, v5, v8
	s_waitcnt lgkmcnt(2)
	v_add_f32_e32 v2, v2, v12
	v_cndmask_b32_e64 v8, v5, v2, s[8:9]
	ds_bpermute_b32 v8, v48, v8
	v_cndmask_b32_e64 v6, v10, v6, s[0:1]
	s_waitcnt lgkmcnt(2)
	v_add_f32_e32 v4, v4, v14
	s_waitcnt lgkmcnt(1)
	v_add_f32_e32 v6, v6, v9
	v_cndmask_b32_e64 v7, v4, v6, s[8:9]
	ds_bpermute_b32 v7, v48, v7
	v_cndmask_b32_e64 v4, v6, v4, s[8:9]
	v_cndmask_b32_e64 v2, v2, v5, s[8:9]
	v_cndmask_b32_e32 v6, v143, v159, vcc
	s_waitcnt lgkmcnt(1)
	v_add_f32_e32 v2, v2, v8
	ds_bpermute_b32 v6, v46, v6
	v_cndmask_b32_e32 v8, v145, v161, vcc
	ds_bpermute_b32 v8, v46, v8
	v_cndmask_b32_e32 v9, v147, v163, vcc
	ds_bpermute_b32 v9, v46, v9
	s_waitcnt lgkmcnt(3)
	v_add_f32_e32 v4, v4, v7
	v_cndmask_b32_e32 v7, v159, v143, vcc
	s_waitcnt lgkmcnt(2)
	v_add_f32_e32 v6, v7, v6
	v_cndmask_b32_e32 v7, v161, v145, vcc
	s_waitcnt lgkmcnt(1)
	v_add_f32_e32 v7, v7, v8
	v_cndmask_b32_e32 v8, v163, v147, vcc
	s_waitcnt lgkmcnt(0)
	v_add_f32_e32 v8, v8, v9
	v_cndmask_b32_e32 v9, v149, v165, vcc
	ds_bpermute_b32 v9, v46, v9
	v_cndmask_b32_e32 v11, v151, v167, vcc
	ds_bpermute_b32 v11, v46, v11
	v_cndmask_b32_e32 v12, v153, v169, vcc
	ds_bpermute_b32 v12, v46, v12
	v_cndmask_b32_e32 v10, v165, v149, vcc
	s_waitcnt lgkmcnt(2)
	v_add_f32_e32 v9, v10, v9
	v_cndmask_b32_e32 v10, v167, v151, vcc
	s_waitcnt lgkmcnt(1)
	v_add_f32_e32 v10, v10, v11
	v_cndmask_b32_e32 v11, v169, v153, vcc
	s_waitcnt lgkmcnt(0)
	v_add_f32_e32 v11, v11, v12
	v_cndmask_b32_e32 v12, v155, v171, vcc
	v_cndmask_b32_e32 v14, v157, v173, vcc
	ds_bpermute_b32 v12, v46, v12
	ds_bpermute_b32 v14, v46, v14
	v_cndmask_b32_e32 v13, v171, v155, vcc
	v_cndmask_b32_e32 v3, v173, v157, vcc
	v_cndmask_b32_e64 v15, v6, v10, s[0:1]
	s_waitcnt lgkmcnt(1)
	v_add_f32_e32 v12, v13, v12
	s_waitcnt lgkmcnt(0)
	v_add_f32_e32 v3, v3, v14
	v_cndmask_b32_e64 v6, v10, v6, s[0:1]
	v_cndmask_b32_e64 v10, v7, v11, s[0:1]
	v_cndmask_b32_e64 v7, v11, v7, s[0:1]
	v_cndmask_b32_e64 v11, v8, v12, s[0:1]
	v_cndmask_b32_e64 v13, v9, v3, s[0:1]
	ds_bpermute_b32 v15, v47, v15
	ds_bpermute_b32 v10, v47, v10
	ds_bpermute_b32 v11, v47, v11
	ds_bpermute_b32 v13, v47, v13
	v_cndmask_b32_e64 v8, v12, v8, s[0:1]
	v_cndmask_b32_e64 v3, v3, v9, s[0:1]
	s_waitcnt lgkmcnt(3)
	v_add_f32_e32 v6, v6, v15
	s_waitcnt lgkmcnt(2)
	v_add_f32_e32 v7, v7, v10
	s_waitcnt lgkmcnt(1)
	v_add_f32_e32 v8, v8, v11
	s_waitcnt lgkmcnt(0)
	v_add_f32_e32 v3, v3, v13
	v_cndmask_b32_e64 v9, v6, v8, s[8:9]
	v_cndmask_b32_e64 v10, v7, v3, s[8:9]
	ds_bpermute_b32 v9, v48, v9
	ds_bpermute_b32 v10, v48, v10
	v_cndmask_b32_e64 v6, v8, v6, s[8:9]
	v_cndmask_b32_e64 v3, v3, v7, s[8:9]
	v_cndmask_b32_e64 v5, v4, v2, s[4:5]
	s_waitcnt lgkmcnt(1)
	v_add_f32_e32 v6, v6, v9
	s_waitcnt lgkmcnt(0)
	v_add_f32_e32 v3, v3, v10
	v_cndmask_b32_e64 v7, v6, v3, s[4:5]
	ds_bpermute_b32 v5, v49, v5
	ds_bpermute_b32 v7, v49, v7
	v_cndmask_b32_e64 v2, v2, v4, s[4:5]
	v_cndmask_b32_e64 v3, v3, v6, s[4:5]
	s_waitcnt lgkmcnt(1)
	v_add_f32_e32 v2, v2, v5
	s_waitcnt lgkmcnt(0)
	v_add_f32_e32 v3, v3, v7
	ds_bpermute_b32 v4, v50, v2
	ds_bpermute_b32 v6, v50, v3
	s_waitcnt lgkmcnt(1)
	v_add_f32_e32 v4, v2, v4
	s_waitcnt lgkmcnt(0)
	v_add_f32_e32 v2, v3, v6
	ds_bpermute_b32 v5, v51, v4
	ds_bpermute_b32 v3, v51, v2
	s_and_saveexec_b64 s[18:19], s[6:7]
	s_cbranch_execz .LBB0_37
	s_waitcnt lgkmcnt(1)
	v_add_f32_e32 v4, v4, v5
	v_add_f32_e32 v4, v1, v4
	v_mul_f32_e64 v5, |v4|, s20
	v_exp_f32_e32 v5, v5
	s_waitcnt lgkmcnt(0)
	v_add_f32_e32 v2, v2, v3
	v_add_f32_e32 v6, v1, v2
	v_max_f32_e32 v4, 0, v4
	v_add_f32_e32 v7, 1.0, v5
	v_add_f32_e32 v2, -1.0, v7
	v_sub_f32_e32 v3, v2, v7
	v_add_f32_e32 v3, 1.0, v3
	v_sub_f32_e32 v2, v5, v2
	v_add_f32_e32 v8, v2, v3
	v_frexp_mant_f32_e32 v9, v7
	v_cvt_f64_f32_e32 v[2:3], v7
	v_frexp_exp_i32_f64_e32 v2, v[2:3]
	v_cmp_gt_f32_e64 s[10:11], s21, v9
	s_nop 1
	v_subbrev_co_u32_e64 v2, s[10:11], 0, v2, s[10:11]
	v_sub_u32_e32 v3, 0, v2
	v_ldexp_f32 v7, v7, v3
	v_ldexp_f32 v3, v8, v3
	v_add_f32_e32 v8, -1.0, v7
	v_add_f32_e32 v11, 1.0, v7
	v_add_f32_e32 v9, 1.0, v8
	v_add_f32_e32 v12, -1.0, v11
	v_sub_f32_e32 v9, v7, v9
	v_sub_f32_e32 v7, v7, v12
	v_add_f32_e32 v9, v3, v9
	v_add_f32_e32 v3, v3, v7
	v_add_f32_e32 v7, v11, v3
	v_rcp_f32_e32 v12, v7
	v_add_f32_e32 v10, v8, v9
	v_sub_f32_e32 v8, v10, v8
	v_sub_f32_e32 v8, v9, v8
	v_sub_f32_e32 v9, v7, v11
	v_sub_f32_e32 v3, v3, v9
	v_mul_f32_e32 v9, v10, v12
	v_mul_f32_e32 v11, v7, v9
	v_fma_f32 v13, v9, v7, -v11
	v_fmac_f32_e32 v13, v9, v3
	v_add_f32_e32 v14, v11, v13
	v_sub_f32_e32 v15, v10, v14
	v_sub_f32_e32 v10, v10, v15
	v_sub_f32_e32 v11, v14, v11
	v_sub_f32_e32 v10, v10, v14
	v_add_f32_e32 v8, v8, v10
	v_sub_f32_e32 v10, v11, v13
	v_add_f32_e32 v8, v10, v8
	v_add_f32_e32 v10, v15, v8
	v_mul_f32_e32 v11, v12, v10
	v_mul_f32_e32 v13, v7, v11
	v_fma_f32 v7, v11, v7, -v13
	v_fmac_f32_e32 v7, v11, v3
	v_sub_f32_e32 v3, v15, v10
	v_add_f32_e32 v3, v8, v3
	v_add_f32_e32 v8, v13, v7
	v_sub_f32_e32 v14, v10, v8
	v_sub_f32_e32 v10, v10, v14
	v_sub_f32_e32 v13, v8, v13
	v_sub_f32_e32 v8, v10, v8
	v_add_f32_e32 v3, v3, v8
	v_sub_f32_e32 v7, v13, v7
	v_cvt_f32_i32_e32 v2, v2
	v_add_f32_e32 v3, v7, v3
	v_add_f32_e32 v7, v9, v11
	v_add_f32_e32 v3, v14, v3
	v_sub_f32_e32 v8, v7, v9
	v_mul_f32_e32 v3, v12, v3
	v_sub_f32_e32 v8, v11, v8
	v_add_f32_e32 v3, v8, v3
	v_mul_f32_e32 v11, 0x3f317218, v2
	v_add_f32_e32 v8, v7, v3
	v_fma_f32 v12, v2, s22, -v11
	v_mul_f32_e32 v9, v8, v8
	v_fmac_f32_e32 v12, 0xb102e308, v2
	v_sub_f32_e32 v2, v8, v7
	v_fmamk_f32 v10, v9, 0x3e9b6dac, v52
	v_sub_f32_e32 v2, v3, v2
	v_add_f32_e32 v3, v11, v12
	v_fmaak_f32 v10, v9, v10, 0x3f2aaada
	v_sub_f32_e32 v7, v3, v11
	v_ldexp_f32 v11, v8, 1
	v_mul_f32_e32 v8, v8, v9
	v_mul_f32_e32 v8, v8, v10
	v_add_f32_e32 v9, v11, v8
	v_sub_f32_e32 v10, v9, v11
	v_ldexp_f32 v2, v2, 1
	v_sub_f32_e32 v8, v8, v10
	v_add_f32_e32 v2, v2, v8
	v_add_f32_e32 v8, v9, v2
	v_sub_f32_e32 v9, v8, v9
	v_sub_f32_e32 v2, v2, v9
	v_add_f32_e32 v9, v3, v8
	v_sub_f32_e32 v10, v9, v3
	v_sub_f32_e32 v11, v9, v10
	v_sub_f32_e32 v7, v12, v7
	v_sub_f32_e32 v3, v3, v11
	v_sub_f32_e32 v8, v8, v10
	v_add_f32_e32 v3, v8, v3
	v_add_f32_e32 v8, v7, v2
	v_sub_f32_e32 v10, v8, v7
	v_sub_f32_e32 v11, v8, v10
	v_sub_f32_e32 v7, v7, v11
	v_sub_f32_e32 v2, v2, v10
	v_add_f32_e32 v3, v8, v3
	v_add_f32_e32 v2, v2, v7
	v_add_f32_e32 v7, v9, v3
	v_sub_f32_e32 v8, v7, v9
	v_sub_f32_e32 v3, v3, v8
	v_add_f32_e32 v2, v2, v3
	v_add_f32_e32 v2, v7, v2
	v_cmp_neq_f32_e64 s[10:11], s23, v5
	s_nop 1
	v_cndmask_b32_e64 v2, v53, v2, s[10:11]
	v_cmp_ngt_f32_e64 s[10:11], -1.0, v5
	s_nop 1
	v_cndmask_b32_e64 v2, v54, v2, s[10:11]
	v_cmp_neq_f32_e64 s[10:11], -1.0, v5
	s_nop 1
	v_cndmask_b32_e64 v2, v55, v2, s[10:11]
	v_cmp_lt_f32_e64 s[10:11], |v5|, s24
	s_nop 1
	v_cndmask_b32_e64 v2, v2, v5, s[10:11]
	v_add_f32_e32 v4, v4, v2
	v_mul_f32_e64 v2, |v6|, s20
	v_exp_f32_e32 v5, v2
	s_lshl_b64 s[10:11], s[16:17], 6
	v_lshl_add_u64 v[2:3], v[38:39], 0, s[10:11]
	global_store_dword v[2:3], v4, off
	v_max_f32_e32 v4, 0, v6
	v_add_f32_e32 v6, 1.0, v5
	v_add_f32_e32 v2, -1.0, v6
	v_sub_f32_e32 v3, v2, v6
	v_add_f32_e32 v3, 1.0, v3
	v_sub_f32_e32 v2, v5, v2
	v_add_f32_e32 v7, v2, v3
	v_frexp_mant_f32_e32 v8, v6
	v_cvt_f64_f32_e32 v[2:3], v6
	v_frexp_exp_i32_f64_e32 v2, v[2:3]
	v_cmp_gt_f32_e64 s[10:11], s21, v8
	s_nop 1
	v_subbrev_co_u32_e64 v2, s[10:11], 0, v2, s[10:11]
	v_sub_u32_e32 v3, 0, v2
	v_ldexp_f32 v6, v6, v3
	v_ldexp_f32 v3, v7, v3
	v_add_f32_e32 v7, -1.0, v6
	v_add_f32_e32 v10, 1.0, v6
	v_add_f32_e32 v8, 1.0, v7
	v_add_f32_e32 v11, -1.0, v10
	v_sub_f32_e32 v8, v6, v8
	v_sub_f32_e32 v6, v6, v11
	v_add_f32_e32 v8, v3, v8
	v_add_f32_e32 v3, v3, v6
	v_add_f32_e32 v6, v10, v3
	v_rcp_f32_e32 v11, v6
	v_add_f32_e32 v9, v7, v8
	v_sub_f32_e32 v7, v9, v7
	v_sub_f32_e32 v7, v8, v7
	v_sub_f32_e32 v8, v6, v10
	v_sub_f32_e32 v3, v3, v8
	v_mul_f32_e32 v8, v9, v11
	v_mul_f32_e32 v10, v6, v8
	v_fma_f32 v12, v8, v6, -v10
	v_fmac_f32_e32 v12, v8, v3
	v_add_f32_e32 v13, v10, v12
	v_sub_f32_e32 v14, v9, v13
	v_sub_f32_e32 v9, v9, v14
	v_sub_f32_e32 v10, v13, v10
	v_sub_f32_e32 v9, v9, v13
	v_add_f32_e32 v7, v7, v9
	v_sub_f32_e32 v9, v10, v12
	v_add_f32_e32 v7, v9, v7
	v_add_f32_e32 v9, v14, v7
	v_mul_f32_e32 v10, v11, v9
	v_mul_f32_e32 v12, v6, v10
	v_fma_f32 v6, v10, v6, -v12
	v_fmac_f32_e32 v6, v10, v3
	v_sub_f32_e32 v3, v14, v9
	v_add_f32_e32 v3, v7, v3
	v_add_f32_e32 v7, v12, v6
	v_sub_f32_e32 v13, v9, v7
	v_sub_f32_e32 v9, v9, v13
	v_sub_f32_e32 v12, v7, v12
	v_sub_f32_e32 v7, v9, v7
	v_add_f32_e32 v3, v3, v7
	v_sub_f32_e32 v6, v12, v6
	v_cvt_f32_i32_e32 v2, v2
	v_add_f32_e32 v3, v6, v3
	v_add_f32_e32 v6, v8, v10
	v_add_f32_e32 v3, v13, v3
	v_sub_f32_e32 v7, v6, v8
	v_mul_f32_e32 v3, v11, v3
	v_sub_f32_e32 v7, v10, v7
	v_add_f32_e32 v3, v7, v3
	v_mul_f32_e32 v10, 0x3f317218, v2
	v_add_f32_e32 v7, v6, v3
	v_fma_f32 v11, v2, s22, -v10
	v_mul_f32_e32 v8, v7, v7
	v_fmac_f32_e32 v11, 0xb102e308, v2
	v_sub_f32_e32 v2, v7, v6
	v_fmamk_f32 v9, v8, 0x3e9b6dac, v52
	v_sub_f32_e32 v2, v3, v2
	v_add_f32_e32 v3, v10, v11
	v_fmaak_f32 v9, v8, v9, 0x3f2aaada
	v_sub_f32_e32 v6, v3, v10
	v_ldexp_f32 v10, v7, 1
	v_mul_f32_e32 v7, v7, v8
	v_mul_f32_e32 v7, v7, v9
	v_add_f32_e32 v8, v10, v7
	v_sub_f32_e32 v9, v8, v10
	v_ldexp_f32 v2, v2, 1
	v_sub_f32_e32 v7, v7, v9
	v_add_f32_e32 v2, v2, v7
	v_add_f32_e32 v7, v8, v2
	v_sub_f32_e32 v8, v7, v8
	v_sub_f32_e32 v2, v2, v8
	v_add_f32_e32 v8, v3, v7
	v_sub_f32_e32 v9, v8, v3
	v_sub_f32_e32 v10, v8, v9
	v_sub_f32_e32 v6, v11, v6
	v_sub_f32_e32 v3, v3, v10
	v_sub_f32_e32 v7, v7, v9
	v_add_f32_e32 v3, v7, v3
	v_add_f32_e32 v7, v6, v2
	v_sub_f32_e32 v9, v7, v6
	v_sub_f32_e32 v10, v7, v9
	v_sub_f32_e32 v6, v6, v10
	v_sub_f32_e32 v2, v2, v9
	v_add_f32_e32 v3, v7, v3
	v_add_f32_e32 v2, v2, v6
	v_add_f32_e32 v6, v8, v3
	v_sub_f32_e32 v7, v6, v8
	v_sub_f32_e32 v3, v3, v7
	v_add_f32_e32 v2, v2, v3
	v_add_f32_e32 v2, v6, v2
	v_cmp_neq_f32_e64 s[10:11], s23, v5
	s_nop 1
	v_cndmask_b32_e64 v2, v53, v2, s[10:11]
	v_cmp_ngt_f32_e64 s[10:11], -1.0, v5
	s_nop 1
	v_cndmask_b32_e64 v2, v54, v2, s[10:11]
	v_cmp_neq_f32_e64 s[10:11], -1.0, v5
	s_nop 1
	v_cndmask_b32_e64 v2, v55, v2, s[10:11]
	v_cmp_lt_f32_e64 s[10:11], |v5|, s24
	s_nop 1
	v_cndmask_b32_e64 v2, v2, v5, s[10:11]
	s_lshl_b64 s[10:11], s[14:15], 6
	v_add_f32_e32 v4, v4, v2
	v_lshl_add_u64 v[2:3], v[38:39], 0, s[10:11]
	global_store_dword v[2:3], v4, off
	s_branch .LBB0_37
